# seams 2 and 3 (GLU -> out-proj -> gate) use per-panel-group arrival counters instead of domain barriers; P7 row-sum exchange through L2-shared {sum,tag} granules
# speedup vs baseline: 1.0139x; 1.0019x over previous
; __device__ __forceinline__ int lane_id() { int l; asm volatile("v_mbcnt_lo_u32_b32 %0, -1, 0\n\tv_mbcnt_hi_u32_b32 %0, -1, %0" : "=v"(l)); return l; }
; __device__ __forceinline__ unsigned xb_add(unsigned* p, unsigned v) { return __hip_atomic_fetch_add(p, v, __ATOMIC_RELAXED, __HIP_MEMORY_SCOPE_AGENT); }
; __device__ __forceinline__ void xcd_arrive(const XcdBarrier& b) {
;     asm volatile("s_waitcnt vmcnt(0)" ::: "memory");
;     __syncthreads();
;     if (b.w0 != 0 && lane_id() == 0) {
;         unsigned* bar = b.bar;
;         __builtin_amdgcn_s_waitcnt(0);
;         unsigned nloc = b.st[0], nx = b.st[1];
;         if (nloc == 0u) { xcd_barrier_complete(bar, b.x, b.G, nloc, nx); b.st[0] = nloc; b.st[1] = nx; }
;         const unsigned old = xb_add(&bar[XB_XSUB(b.x)], 1u);
;         const unsigned gen = old / nloc;
;         if (old + 1u == (gen + 1u) * nloc) {
;             __builtin_amdgcn_fence(__ATOMIC_RELEASE, "agent");
;             asm volatile("s_waitcnt vmcnt(0)" ::: "memory");
;             const unsigned og = xb_add(&bar[XB_TOP], 1u);
;             const unsigned tg = og / nx;
;             if (og + 1u == (tg + 1u) * nx) xb_add(&bar[XB_TOPGEN], 1u);
;         }
;     }
; template <int UPTO>
; __device__ __forceinline__ void program(Frame& F, const XcdBarrier& bar, const XcdBarrier& gbar, const XcdBarrier& sbar, const int half, const int xl, const int jx) {
;     ...
;         xcd_arrive(sbar);
.LBB0_456:
	s_waitcnt vmcnt(0)
	s_barrier
	s_waitcnt vmcnt(0)
	s_and_b64 vcc, exec, s[94:95]
	s_barrier
	s_cbranch_vccnz .LBB0_482
	v_mbcnt_lo_u32_b32 v0, -1, 0
	v_mbcnt_hi_u32_b32 v0, -1, v0
	s_nop 0
	v_cmp_eq_u32_e32 vcc, 0, v0
	s_and_saveexec_b64 s[4:5], vcc
	s_cbranch_execz .LBB0_481
	v_readlane_b32 s0, v254, 19
	v_readlane_b32 s1, v254, 21
	s_add_i32 s0, s0, s1
	s_lshl_b32 s0, s0, 7
	s_add_u32 s0, s0, 0x7000
	v_mov_b32_e32 v0, s0
	v_mov_b32_e32 v1, 1
	global_atomic_add v0, v1, s[52:53]

; __device__ __forceinline__ int lane_id() { int l; asm volatile("v_mbcnt_lo_u32_b32 %0, -1, 0\n\tv_mbcnt_hi_u32_b32 %0, -1, %0" : "=v"(l)); return l; }
; __device__ __forceinline__ unsigned xb_ld(unsigned* p)              { return __hip_atomic_load(p, __ATOMIC_RELAXED, __HIP_MEMORY_SCOPE_AGENT); }
; #define XB_SPIN(cond, bar) do { unsigned _sp = 0; while (cond) { __builtin_amdgcn_s_sleep(1); \
;     if ((++_sp & 255u) == 0u) { if (xb_ld(&(bar)[XB_TMO])) break; if (_sp > XB_SPIN_CAP) { atomicAdd(&(bar)[XB_TMO], 1u); break; } } } } while (0)
; __device__ __forceinline__ void xcd_wait2(const XcdBarrier& b, unsigned use, unsigned* obar, unsigned ouse) {
;     if (b.w0 != 0 && lane_id() == 0) {
;         unsigned* bar = b.bar;
;         XB_SPIN(xb_ld(&obar[XB_TOPGEN]) <= ouse, bar);
;         XB_SPIN(xb_ld(&bar[XB_TOPGEN]) <= use, bar);
;         __builtin_amdgcn_fence(__ATOMIC_ACQUIRE, "agent");
;         asm volatile("s_waitcnt vmcnt(0)" ::: "memory");
;     }
;     __syncthreads();
.LBB0_501:
	v_readlane_b32 s38, v254, 19
	v_readlane_b32 s39, v254, 21
	s_add_i32 s38, s38, s39
	s_lshl_b32 s38, s38, 7
	s_add_u32 s38, s38, 0x7000
	v_mov_b32_e32 v0, s38
	s_movk_i32 s0, 0x4000
.Lpn2_poll:
	global_load_dword v1, v0, s[52:53] sc1
	s_waitcnt vmcnt(0)
	v_cmp_lt_u32_e32 vcc, 7, v1
	s_cbranch_vccnz .Lpn2_got
	s_sleep 1
	s_sub_u32 s0, s0, 1
	s_cmp_lg_u32 s0, 0
	s_cbranch_scc1 .Lpn2_poll
.Lpn2_got:
.LBB0_514:
	s_waitcnt vmcnt(0)
	buffer_inv sc1
	s_waitcnt vmcnt(0)
.LBB0_515:
	s_or_b64 exec, exec, s[14:15]
